# E33 PF pre-loop: three serialized branch-norm sum loads issued together before one wait
# speedup vs baseline: 1.0051x; 1.0024x over previous
; #define LAS __attribute__((address_space(3)))
; __global__ void __launch_bounds__(NWAVES * 64, 2) fwd_kernel(KArgs a) {
;     ...
;             { pg8::Unit u0; const int tl = wave * 64 + ln;
;               if (S.next(0, u0) && tl < 256) {
;                   const int row = u0.pm * 256 + tl;
;                   const float r1 = __builtin_amdgcn_rsqf(SSP(l, SS_SB)[row] * (1.f / 512.f) + EPS), r2 = __builtin_amdgcn_rsqf(SSP(l, SS_CONV)[row] * (1.f / 256.f) + EPS), r3 = __builtin_amdgcn_rsqf(SSP(l, SS_SSM)[row] * (1.f / 256.f) + EPS);
;                   LAS float* fac = (LAS float*)(lds + EX_OFF) + tl * 4;
;                   fac[0] = r1 / r2; fac[1] = r2 / r3; fac[2] = r3; }
;               __syncthreads(); }
.LBB0_733:
	v_readlane_b32 s0, v254, 45
	s_nop 1
	v_add_u32_e32 v0, s0, v0
	s_movk_i32 s0, 0x100
	v_cmp_gt_i32_e32 vcc, s0, v0
	s_and_b64 s[6:7], s[4:5], vcc
	s_and_saveexec_b64 s[0:1], s[6:7]
	s_cbranch_execz .LBB0_735
	v_readlane_b32 s6, v215, 47
	s_waitcnt lgkmcnt(0)
	s_nop 0
	v_lshl_add_u32 v2, s6, 8, v0
	v_readlane_b32 s6, v215, 45
	v_readlane_b32 s7, v215, 46
	s_lshl_b64 s[6:7], s[6:7], 2
	s_add_u32 s6, s2, s6
	s_addc_u32 s7, s3, s7
	v_ashrrev_i32_e32 v3, 31, v2
	v_lshl_add_u64 v[2:3], v[2:3], 2, s[6:7]
	v_add_co_u32_e32 v4, vcc, 0x10000, v2
	v_lshl_add_u32 v0, v0, 4, 0
	s_nop 0
	v_addc_co_u32_e32 v5, vcc, 0, v3, vcc
	global_load_dword v1, v[4:5], off
	v_add_co_u32_e32 v4, vcc, 0x20000, v2
	s_nop 1
	v_addc_co_u32_e32 v5, vcc, 0, v3, vcc
	global_load_dword v7, v[4:5], off
	v_add_co_u32_e32 v2, vcc, 0x30000, v2
	s_nop 1
	v_addc_co_u32_e32 v3, vcc, 0, v3, vcc
	global_load_dword v8, v[2:3], off
	v_add_u32_e32 v3, 0x21000, v0
	s_waitcnt vmcnt(0)
	v_fmamk_f32 v1, v1, 0x3b000000, v212
	v_fmamk_f32 v7, v7, 0x3b800000, v212
	v_fmamk_f32 v8, v8, 0x3b800000, v212
	v_rsq_f32_e32 v6, v1
	v_rsq_f32_e32 v4, v7
	v_rsq_f32_e32 v2, v8
	s_nop 0
	v_div_scale_f32 v0, s[6:7], v2, v2, v4
	v_rcp_f32_e32 v1, v0
	s_nop 0
	v_fma_f32 v5, -v0, v1, 1.0
	v_fmac_f32_e32 v1, v5, v1
	v_div_scale_f32 v5, vcc, v4, v2, v4
	v_mul_f32_e32 v7, v5, v1
	v_fma_f32 v8, -v0, v7, v5
	v_fmac_f32_e32 v7, v8, v1
	v_fma_f32 v0, -v0, v7, v5
	v_div_fmas_f32 v0, v0, v1, v7
	v_div_fixup_f32 v1, v0, v2, v4
	v_div_scale_f32 v0, s[6:7], v4, v4, v6
	v_rcp_f32_e32 v5, v0
	s_nop 0
	v_fma_f32 v7, -v0, v5, 1.0
	v_fmac_f32_e32 v5, v7, v5
	v_div_scale_f32 v7, vcc, v6, v4, v6
	v_mul_f32_e32 v8, v7, v5
	v_fma_f32 v9, -v0, v8, v7
	v_fmac_f32_e32 v8, v9, v5
	v_fma_f32 v0, -v0, v8, v7
	v_div_fmas_f32 v0, v0, v5, v8
	v_div_fixup_f32 v0, v0, v4, v6
	ds_write_b96 v3, v[0:2]
